# diff-attention pass-2 epilogue: xor1/xor2 sub-LN reduction rounds via DPP quad_perm moves
# speedup vs baseline: 1.0007x; 1.0007x over previous
; template <int THRL> ...
;     ...
;         for (int r = 0; r < 16; r += 2) { const unsigned w = ((const unsigned*)scr)[(d0 * 8 + (r >> 1)) * 64];
;           const float v0 = __uint_as_float(w << 16) - lam * (o[d0][r] * rli[r]), v1 = __uint_as_float(w & 0xffff0000u) - lam * (o[d0][r + 1] * rli[r + 1]);
;           o[d0][r] = v0; o[d0][r + 1] = v1; ss[r] += v0 * v0; ss[r + 1] += v1 * v1; }
;     ...
;       const unsigned gd_ = need ? __hip_atomic_load(guard, __ATOMIC_RELAXED, __HIP_MEMORY_SCOPE_AGENT) : 0u;
;       float g[4];
; #pragma unroll
;       for (int d0 = 0; d0 < 4; ++d0) g[d0] = subg[d0 * 32 + r32_o];
.LBB0_481:
	global_load_dword v244, v147, s[12:13] sc1
	v_mov_b32_e32 v250, v70
	v_ashrrev_i32_e32 v251, 31, v70
	v_lshl_add_u64 v[250:251], v[250:251], 2, s[22:23]
	global_load_dword v245, v[250:251], off
	global_load_dword v246, v[250:251], off offset:128
	global_load_dword v247, v[250:251], off offset:256
	global_load_dword v248, v[250:251], off offset:384
	global_load_dword v26, v[66:67], off
	global_load_dword v27, v[66:67], off offset:256
	global_load_dword v28, v[66:67], off offset:512
	global_load_dword v29, v[66:67], off offset:768
	global_load_dword v30, v[66:67], off offset:1024
	global_load_dword v31, v[66:67], off offset:1280
	global_load_dword v32, v[66:67], off offset:1536
	global_load_dword v33, v[66:67], off offset:1792
	global_load_dword v40, v[66:67], off offset:2048
	global_load_dword v41, v[66:67], off offset:2304
	global_load_dword v42, v[66:67], off offset:2560
	global_load_dword v44, v[66:67], off offset:2816
	global_load_dword v45, v[66:67], off offset:3072
	global_load_dword v71, v[66:67], off offset:3328
	global_load_dword v97, v[66:67], off offset:3584
	global_load_dword v100, v[66:67], off offset:3840
	v_add_co_u32_e32 v106, vcc, s78, v66
	s_mov_b64 s[28:29], 0
	s_nop 0
	v_addc_co_u32_e32 v107, vcc, 0, v67, vcc
	global_load_dword v103, v[106:107], off
	global_load_dword v109, v[106:107], off offset:256
	global_load_dword v110, v[106:107], off offset:512
	global_load_dword v111, v[106:107], off offset:768
	global_load_dword v112, v[106:107], off offset:1024
	global_load_dword v114, v[106:107], off offset:1280
	global_load_dword v209, v[106:107], off offset:3584
	s_and_b64 vcc, exec, s[4:5]
	global_load_dword v122, v[106:107], off offset:1792
	global_load_dword v126, v[106:107], off offset:2048
	global_load_dword v130, v[106:107], off offset:2304
	global_load_dword v133, v[106:107], off offset:2560
	global_load_dword v204, v[106:107], off offset:2816
	global_load_dword v205, v[106:107], off offset:3072
	global_load_dword v208, v[106:107], off offset:3328
	s_waitcnt vmcnt(29)
	v_lshlrev_b32_e32 v43, 16, v26
	v_and_b32_e32 v26, 0xffff0000, v26
	v_fma_f32 v102, -v186, v79, v26
	s_waitcnt vmcnt(28)
	v_lshlrev_b32_e32 v46, 16, v27
	s_waitcnt vmcnt(25)
	v_lshlrev_b32_e32 v49, 16, v30
	v_and_b32_e32 v30, 0xffff0000, v30
	s_waitcnt vmcnt(24)
	v_and_b32_e32 v65, 0xffff0000, v31
	s_waitcnt vmcnt(23)
	v_lshlrev_b32_e32 v93, 16, v32
	v_and_b32_e32 v95, 0xffff0000, v32
	v_fma_f32 v32, -v186, v83, v30
	v_fma_f32 v30, -v186, v84, v65
	s_waitcnt vmcnt(18)
	v_lshlrev_b32_e32 v118, 16, v44
	v_fma_f32 v65, -v186, v53, v118
	global_load_dword v118, v[106:107], off offset:1536
	v_lshlrev_b32_e32 v98, 16, v33
	global_load_dword v107, v[106:107], off offset:3840
	v_and_b32_e32 v33, 0xffff0000, v33
	v_lshlrev_b32_e32 v64, 16, v31
	v_fma_f32 v26, -v186, v86, v33
	v_and_b32_e32 v33, 0xffff0000, v44
	v_fma_f32 v31, -v186, v76, v64
	v_fma_f32 v64, -v186, v90, v33
	s_waitcnt vmcnt(19)
	v_lshlrev_b32_e32 v33, 16, v45
	v_lshlrev_b32_e32 v48, 16, v29
	v_lshlrev_b32_e32 v101, 16, v40
	v_and_b32_e32 v104, 0xffff0000, v40
	v_fma_f32 v40, -v186, v75, v49
	v_fma_f32 v49, -v186, v54, v33
	v_and_b32_e32 v33, 0xffff0000, v45
	v_lshlrev_b32_e32 v47, 16, v28
	v_fma_f32 v99, -v186, v72, v46
	v_fma_f32 v46, -v186, v74, v48
	v_fma_f32 v48, -v186, v59, v33
	s_waitcnt vmcnt(18)
	v_lshlrev_b32_e32 v33, 16, v71
	v_fma_f32 v94, -v186, v73, v47
	v_fma_f32 v47, -v186, v55, v33
	v_and_b32_e32 v33, 0xffff0000, v71
	v_fma_f32 v45, -v186, v60, v33
	s_waitcnt vmcnt(17)
	v_lshlrev_b32_e32 v33, 16, v97
	v_fma_f32 v44, -v186, v56, v33
	v_and_b32_e32 v33, 0xffff0000, v97
	s_waitcnt vmcnt(15)
	v_lshlrev_b32_e32 v97, 16, v103
	v_fma_f32 v138, -v186, v58, v97
	v_and_b32_e32 v97, 0xffff0000, v103
	v_fma_f32 v136, -v186, v63, v97
	s_waitcnt vmcnt(14)
	v_lshlrev_b32_e32 v97, 16, v109
	v_fma_f32 v134, -v186, v2, v97
	v_and_b32_e32 v97, 0xffff0000, v109
	v_fma_f32 v132, -v186, v17, v97
	s_waitcnt vmcnt(13)
	v_lshlrev_b32_e32 v97, 16, v110
	v_fma_f32 v131, -v186, v3, v97
	v_and_b32_e32 v97, 0xffff0000, v110
	v_fma_f32 v127, -v186, v34, v97
	s_waitcnt vmcnt(12)
	v_lshlrev_b32_e32 v97, 16, v111
	v_fma_f32 v123, -v186, v4, v97
	v_and_b32_e32 v97, 0xffff0000, v111
	v_and_b32_e32 v28, 0xffff0000, v28
	v_lshlrev_b32_e32 v115, 16, v42
	v_fma_f32 v119, -v186, v35, v97
	s_waitcnt vmcnt(11)
	v_lshlrev_b32_e32 v97, 16, v112
	v_lshlrev_b32_e32 v113, 16, v41
	v_fma_f32 v92, -v186, v81, v28
	v_fma_f32 v28, -v186, v85, v95
	v_fma_f32 v95, -v186, v52, v115
	v_fma_f32 v115, -v186, v5, v97
	v_and_b32_e32 v97, 0xffff0000, v112
	v_fma_f32 v108, -v186, v50, v101
	v_fma_f32 v101, -v186, v51, v113
	v_fma_f32 v113, -v186, v36, v97
	s_waitcnt vmcnt(10)
	v_lshlrev_b32_e32 v97, 16, v114
	v_fma_f32 v111, -v186, v6, v97
	v_and_b32_e32 v97, 0xffff0000, v114
	v_fma_f32 v109, -v186, v37, v97
	v_and_b32_e32 v29, 0xffff0000, v29
	v_and_b32_e32 v42, 0xffff0000, v42
	v_and_b32_e32 v27, 0xffff0000, v27
	v_and_b32_e32 v41, 0xffff0000, v41
	v_fma_f32 v105, -v186, v69, v43
	v_fma_f32 v43, -v186, v82, v29
	v_fma_f32 v29, -v186, v77, v93
	v_fma_f32 v93, -v186, v89, v42
	v_fma_f32 v42, -v186, v61, v33
	v_lshlrev_b32_e32 v33, 16, v100
	v_fma_f32 v96, -v186, v80, v27
	v_fma_f32 v27, -v186, v78, v98
	v_fma_f32 v98, -v186, v88, v41
	v_fma_f32 v41, -v186, v57, v33
	v_and_b32_e32 v33, 0xffff0000, v100
	v_fma_f32 v104, -v186, v87, v104
	v_fma_f32 v33, -v186, v62, v33
	v_mul_f32_e32 v142, v108, v108
	v_mul_f32_e32 v143, v104, v104
	s_waitcnt vmcnt(7)
	v_lshlrev_b32_e32 v110, 16, v126
	v_fma_f32 v146, -v186, v9, v110
	v_and_b32_e32 v110, 0xffff0000, v126
	v_fma_f32 v145, -v186, v18, v110
	s_waitcnt vmcnt(6)
; template <int THRL> ...
;     ...
;         for (int r = 0; r < 16; r += 2) { const unsigned w = ((const unsigned*)scr)[(d0 * 8 + (r >> 1)) * 64];
;           const float v0 = __uint_as_float(w << 16) - lam * (o[d0][r] * rli[r]), v1 = __uint_as_float(w & 0xffff0000u) - lam * (o[d0][r + 1] * rli[r + 1]);
;           o[d0][r] = v0; o[d0][r + 1] = v1; ss[r] += v0 * v0; ss[r + 1] += v1 * v1; }
; #pragma unroll
;       for (int m_ = 1; m_ < 32; m_ <<= 1) {
;         float t_[16];
; #pragma unroll
;         for (int r = 0; r < 16; ++r) t_[r] = __shfl_xor(ss[r], m_);
; #pragma unroll
;         for (int r = 0; r < 16; ++r) ss[r] += t_[r];
	v_lshlrev_b32_e32 v110, 16, v130
	v_fma_f32 v141, -v186, v10, v110
	v_and_b32_e32 v110, 0xffff0000, v130
	v_fma_f32 v140, -v186, v19, v110
	s_waitcnt vmcnt(5)
	v_lshlrev_b32_e32 v110, 16, v133
	v_fma_f32 v139, -v186, v11, v110
	v_and_b32_e32 v110, 0xffff0000, v133
	v_fma_f32 v137, -v186, v20, v110
	s_waitcnt vmcnt(4)
	v_lshlrev_b32_e32 v110, 16, v204
	v_fma_f32 v135, -v186, v12, v110
	v_and_b32_e32 v110, 0xffff0000, v204
	s_waitcnt vmcnt(1)
	v_lshlrev_b32_e32 v97, 16, v118
	v_fma_f32 v133, -v186, v21, v110
	v_lshlrev_b32_e32 v110, 16, v205
	v_fma_f32 v106, -v186, v7, v97
	v_and_b32_e32 v97, 0xffff0000, v118
	v_fma_f32 v130, -v186, v13, v110
	v_and_b32_e32 v110, 0xffff0000, v205
	v_fma_f32 v103, -v186, v38, v97
	v_lshlrev_b32_e32 v97, 16, v122
	v_fma_f32 v126, -v186, v22, v110
	v_lshlrev_b32_e32 v110, 16, v208
	v_fma_f32 v100, -v186, v8, v97
	v_and_b32_e32 v97, 0xffff0000, v122
	v_fma_f32 v122, -v186, v14, v110
	v_and_b32_e32 v110, 0xffff0000, v208
	v_fma_f32 v118, -v186, v23, v110
	v_lshlrev_b32_e32 v110, 16, v209
	v_mul_f32_e32 v144, v101, v101
	v_mul_f32_e32 v149, v98, v98
	v_mul_f32_e32 v176, v95, v95
	v_mul_f32_e32 v177, v93, v93
	v_mul_f32_e32 v178, v65, v65
	v_mul_f32_e32 v179, v64, v64
	v_mul_f32_e32 v180, v49, v49
	v_mul_f32_e32 v181, v48, v48
	v_mul_f32_e32 v71, v47, v47
	v_mul_f32_e32 v201, v45, v45
	v_mul_f32_e32 v202, v44, v44
	v_mul_f32_e32 v203, v42, v42
	v_mul_f32_e32 v206, v41, v41
	v_mul_f32_e32 v207, v33, v33
	v_fma_f32 v114, -v186, v15, v110
	v_and_b32_e32 v110, 0xffff0000, v209
	v_fmac_f32_e32 v142, v105, v105
	v_fmac_f32_e32 v143, v102, v102
	v_fmac_f32_e32 v144, v99, v99
	v_fmac_f32_e32 v149, v96, v96
	v_fmac_f32_e32 v176, v94, v94
	v_fmac_f32_e32 v177, v92, v92
	v_fmac_f32_e32 v178, v46, v46
	v_fmac_f32_e32 v179, v43, v43
	v_fmac_f32_e32 v180, v40, v40
	v_fmac_f32_e32 v181, v32, v32
	v_fmac_f32_e32 v71, v31, v31
	v_fmac_f32_e32 v201, v30, v30
	v_fmac_f32_e32 v202, v29, v29
	v_fmac_f32_e32 v203, v28, v28
	v_fmac_f32_e32 v206, v27, v27
	v_fmac_f32_e32 v207, v26, v26
	v_fma_f32 v97, -v186, v39, v97
	v_fma_f32 v112, -v186, v24, v110
	s_waitcnt vmcnt(0)
	v_lshlrev_b32_e32 v110, 16, v107
	v_and_b32_e32 v107, 0xffff0000, v107
	v_fmac_f32_e32 v142, v138, v138
	v_fmac_f32_e32 v143, v136, v136
	v_fmac_f32_e32 v144, v134, v134
	v_fmac_f32_e32 v149, v132, v132
	v_fmac_f32_e32 v176, v131, v131
	v_fmac_f32_e32 v177, v127, v127
	v_fmac_f32_e32 v178, v123, v123
	v_fmac_f32_e32 v179, v119, v119
	v_fmac_f32_e32 v180, v115, v115
	v_fmac_f32_e32 v181, v113, v113
	v_fmac_f32_e32 v71, v111, v111
	v_fmac_f32_e32 v201, v109, v109
	v_fmac_f32_e32 v202, v106, v106
	v_fmac_f32_e32 v203, v103, v103
	v_fmac_f32_e32 v206, v100, v100
	v_fmac_f32_e32 v207, v97, v97
	v_fma_f32 v110, -v186, v16, v110
	v_fma_f32 v107, -v186, v25, v107
	v_fmac_f32_e32 v142, v146, v146
	v_fmac_f32_e32 v143, v145, v145
	v_fmac_f32_e32 v144, v141, v141
	v_fmac_f32_e32 v149, v140, v140
	v_fmac_f32_e32 v176, v139, v139
	v_fmac_f32_e32 v177, v137, v137
	v_fmac_f32_e32 v178, v135, v135
	v_fmac_f32_e32 v179, v133, v133
	v_fmac_f32_e32 v180, v130, v130
	v_fmac_f32_e32 v181, v126, v126
	v_fmac_f32_e32 v71, v122, v122
	v_fmac_f32_e32 v201, v118, v118
	v_fmac_f32_e32 v202, v114, v114
	v_fmac_f32_e32 v203, v112, v112
	v_fmac_f32_e32 v206, v110, v110
	v_fmac_f32_e32 v207, v107, v107
	v_mov_b32_dpp v204, v142 quad_perm:[1,0,3,2] row_mask:0xf bank_mask:0xf
	v_mov_b32_dpp v205, v143 quad_perm:[1,0,3,2] row_mask:0xf bank_mask:0xf
	v_mov_b32_dpp v208, v144 quad_perm:[1,0,3,2] row_mask:0xf bank_mask:0xf
	v_mov_b32_dpp v209, v149 quad_perm:[1,0,3,2] row_mask:0xf bank_mask:0xf
	v_mov_b32_dpp v210, v176 quad_perm:[1,0,3,2] row_mask:0xf bank_mask:0xf
	v_mov_b32_dpp v211, v177 quad_perm:[1,0,3,2] row_mask:0xf bank_mask:0xf
	v_mov_b32_dpp v212, v178 quad_perm:[1,0,3,2] row_mask:0xf bank_mask:0xf
	v_mov_b32_dpp v213, v179 quad_perm:[1,0,3,2] row_mask:0xf bank_mask:0xf
	v_mov_b32_dpp v214, v180 quad_perm:[1,0,3,2] row_mask:0xf bank_mask:0xf
	v_mov_b32_dpp v215, v181 quad_perm:[1,0,3,2] row_mask:0xf bank_mask:0xf
	v_mov_b32_dpp v216, v71 quad_perm:[1,0,3,2] row_mask:0xf bank_mask:0xf
	v_mov_b32_dpp v217, v201 quad_perm:[1,0,3,2] row_mask:0xf bank_mask:0xf
	v_mov_b32_dpp v218, v202 quad_perm:[1,0,3,2] row_mask:0xf bank_mask:0xf
	v_mov_b32_dpp v219, v203 quad_perm:[1,0,3,2] row_mask:0xf bank_mask:0xf
	v_mov_b32_dpp v220, v206 quad_perm:[1,0,3,2] row_mask:0xf bank_mask:0xf
	v_mov_b32_dpp v221, v207 quad_perm:[1,0,3,2] row_mask:0xf bank_mask:0xf
	s_waitcnt lgkmcnt(14)
	v_add_f32_e32 v142, v142, v204
	v_add_f32_e32 v143, v143, v205
	s_waitcnt lgkmcnt(13)
	v_add_f32_e32 v144, v144, v208
	s_waitcnt lgkmcnt(12)
	v_add_f32_e32 v149, v149, v209
	s_waitcnt lgkmcnt(11)
	v_add_f32_e32 v176, v176, v210
	s_waitcnt lgkmcnt(10)
	v_add_f32_e32 v177, v177, v211
	s_waitcnt lgkmcnt(9)
	v_add_f32_e32 v178, v178, v212
	s_waitcnt lgkmcnt(8)
	v_add_f32_e32 v179, v179, v213
	s_waitcnt lgkmcnt(7)
	v_add_f32_e32 v180, v180, v214
	s_waitcnt lgkmcnt(6)
	v_add_f32_e32 v181, v181, v215
	s_waitcnt lgkmcnt(5)
	v_add_f32_e32 v71, v71, v216
	s_waitcnt lgkmcnt(4)
	v_add_f32_e32 v201, v201, v217
	s_waitcnt lgkmcnt(3)
	v_add_f32_e32 v202, v202, v218
	s_waitcnt lgkmcnt(2)
	v_add_f32_e32 v203, v203, v219
	s_waitcnt lgkmcnt(1)
	v_add_f32_e32 v204, v206, v220
	s_waitcnt lgkmcnt(0)
; template <int THRL> ...
;     ...
; #pragma unroll
;       for (int m_ = 1; m_ < 32; m_ <<= 1) {
;         float t_[16];
; #pragma unroll
;         for (int r = 0; r < 16; ++r) t_[r] = __shfl_xor(ss[r], m_);
; #pragma unroll
;         for (int r = 0; r < 16; ++r) ss[r] += t_[r];
;       }
;     ...
;       const unsigned gd_ = need ? __hip_atomic_load(guard, __ATOMIC_RELAXED, __HIP_MEMORY_SCOPE_AGENT) : 0u;
;       float g[4];
; #pragma unroll
;       for (int d0 = 0; d0 < 4; ++d0) g[d0] = subg[d0 * 32 + r32_o];
;       if (gd_ < need) { unsigned sp_ = 0u; while (__hip_atomic_load(guard, __ATOMIC_RELAXED, __HIP_MEMORY_SCOPE_AGENT) < need && ++sp_ < (1u << 22)) __builtin_amdgcn_s_sleep(2); }
	v_add_f32_e32 v205, v207, v221
	v_mov_b32_dpp v206, v142 quad_perm:[2,3,0,1] row_mask:0xf bank_mask:0xf
	v_mov_b32_dpp v207, v143 quad_perm:[2,3,0,1] row_mask:0xf bank_mask:0xf
	v_mov_b32_dpp v208, v144 quad_perm:[2,3,0,1] row_mask:0xf bank_mask:0xf
	v_mov_b32_dpp v209, v149 quad_perm:[2,3,0,1] row_mask:0xf bank_mask:0xf
	v_mov_b32_dpp v210, v176 quad_perm:[2,3,0,1] row_mask:0xf bank_mask:0xf
	v_mov_b32_dpp v211, v177 quad_perm:[2,3,0,1] row_mask:0xf bank_mask:0xf
	v_mov_b32_dpp v212, v178 quad_perm:[2,3,0,1] row_mask:0xf bank_mask:0xf
	v_mov_b32_dpp v213, v179 quad_perm:[2,3,0,1] row_mask:0xf bank_mask:0xf
	v_mov_b32_dpp v214, v180 quad_perm:[2,3,0,1] row_mask:0xf bank_mask:0xf
	v_mov_b32_dpp v215, v181 quad_perm:[2,3,0,1] row_mask:0xf bank_mask:0xf
	v_mov_b32_dpp v216, v71 quad_perm:[2,3,0,1] row_mask:0xf bank_mask:0xf
	v_mov_b32_dpp v217, v201 quad_perm:[2,3,0,1] row_mask:0xf bank_mask:0xf
	v_mov_b32_dpp v218, v202 quad_perm:[2,3,0,1] row_mask:0xf bank_mask:0xf
	v_mov_b32_dpp v219, v203 quad_perm:[2,3,0,1] row_mask:0xf bank_mask:0xf
	v_mov_b32_dpp v220, v204 quad_perm:[2,3,0,1] row_mask:0xf bank_mask:0xf
	v_mov_b32_dpp v221, v205 quad_perm:[2,3,0,1] row_mask:0xf bank_mask:0xf
	s_waitcnt lgkmcnt(14)
	v_add_f32_e32 v142, v142, v206
	v_add_f32_e32 v143, v143, v207
	s_waitcnt lgkmcnt(13)
	v_add_f32_e32 v144, v144, v208
	s_waitcnt lgkmcnt(12)
	v_add_f32_e32 v149, v149, v209
	s_waitcnt lgkmcnt(11)
	v_add_f32_e32 v176, v176, v210
	s_waitcnt lgkmcnt(10)
	v_add_f32_e32 v177, v177, v211
	s_waitcnt lgkmcnt(9)
	v_add_f32_e32 v178, v178, v212
	s_waitcnt lgkmcnt(8)
	v_add_f32_e32 v179, v179, v213
	s_waitcnt lgkmcnt(7)
	v_add_f32_e32 v180, v180, v214
	s_waitcnt lgkmcnt(6)
	v_add_f32_e32 v181, v181, v215
	s_waitcnt lgkmcnt(5)
	v_add_f32_e32 v71, v71, v216
	s_waitcnt lgkmcnt(4)
	v_add_f32_e32 v201, v201, v217
	s_waitcnt lgkmcnt(3)
	v_add_f32_e32 v202, v202, v218
	s_waitcnt lgkmcnt(2)
	v_add_f32_e32 v203, v203, v219
	s_waitcnt lgkmcnt(1)
	v_add_f32_e32 v204, v204, v220
	s_waitcnt lgkmcnt(0)
	v_add_f32_e32 v205, v205, v221
	ds_bpermute_b32 v206, v183, v142
	ds_bpermute_b32 v207, v183, v143
	ds_bpermute_b32 v208, v183, v144
	ds_bpermute_b32 v209, v183, v149
	ds_bpermute_b32 v210, v183, v176
	ds_bpermute_b32 v211, v183, v177
	ds_bpermute_b32 v212, v183, v178
	ds_bpermute_b32 v213, v183, v179
	ds_bpermute_b32 v214, v183, v180
	ds_bpermute_b32 v215, v183, v181
	ds_bpermute_b32 v216, v183, v71
	ds_bpermute_b32 v217, v183, v201
	ds_bpermute_b32 v218, v183, v202
	ds_bpermute_b32 v219, v183, v203
	ds_bpermute_b32 v220, v183, v204
	ds_bpermute_b32 v221, v183, v205
	s_waitcnt lgkmcnt(14)
	v_add_f32_e32 v142, v142, v206
	v_add_f32_e32 v143, v143, v207
	s_waitcnt lgkmcnt(13)
	v_add_f32_e32 v144, v144, v208
	s_waitcnt lgkmcnt(12)
	v_add_f32_e32 v206, v149, v209
	s_waitcnt lgkmcnt(11)
	v_add_f32_e32 v207, v176, v210
	s_waitcnt lgkmcnt(10)
	v_add_f32_e32 v208, v177, v211
	s_waitcnt lgkmcnt(9)
	v_add_f32_e32 v209, v178, v212
	s_waitcnt lgkmcnt(8)
	v_add_f32_e32 v210, v179, v213
	s_waitcnt lgkmcnt(7)
	v_add_f32_e32 v211, v180, v214
	s_waitcnt lgkmcnt(6)
	v_add_f32_e32 v212, v181, v215
	s_waitcnt lgkmcnt(5)
	v_add_f32_e32 v71, v71, v216
	s_waitcnt lgkmcnt(4)
	v_add_f32_e32 v213, v201, v217
	s_waitcnt lgkmcnt(3)
	v_add_f32_e32 v214, v202, v218
	s_waitcnt lgkmcnt(2)
	v_add_f32_e32 v215, v203, v219
	s_waitcnt lgkmcnt(1)
	v_add_f32_e32 v216, v204, v220
	s_waitcnt lgkmcnt(0)
	v_add_f32_e32 v217, v205, v221
	ds_bpermute_b32 v149, v184, v142
	ds_bpermute_b32 v176, v184, v143
	ds_bpermute_b32 v177, v184, v144
	ds_bpermute_b32 v178, v184, v206
	ds_bpermute_b32 v179, v184, v207
	ds_bpermute_b32 v180, v184, v208
	ds_bpermute_b32 v181, v184, v209
	ds_bpermute_b32 v201, v184, v210
	ds_bpermute_b32 v202, v184, v211
	ds_bpermute_b32 v203, v184, v212
	ds_bpermute_b32 v204, v184, v71
	ds_bpermute_b32 v205, v184, v213
	ds_bpermute_b32 v218, v184, v214
	ds_bpermute_b32 v219, v184, v215
	ds_bpermute_b32 v220, v184, v216
	ds_bpermute_b32 v221, v184, v217
	s_waitcnt lgkmcnt(14)
	v_add_f32_e32 v149, v142, v149
	v_add_f32_e32 v176, v143, v176
	s_waitcnt lgkmcnt(13)
	v_add_f32_e32 v177, v144, v177
	s_waitcnt lgkmcnt(12)
	v_add_f32_e32 v178, v206, v178
	s_waitcnt lgkmcnt(11)
	v_add_f32_e32 v179, v207, v179
	s_waitcnt lgkmcnt(10)
	v_add_f32_e32 v180, v208, v180
	s_waitcnt lgkmcnt(9)
	v_add_f32_e32 v181, v209, v181
	s_waitcnt lgkmcnt(8)
	v_add_f32_e32 v201, v210, v201
	s_waitcnt lgkmcnt(7)
	v_add_f32_e32 v202, v211, v202
	s_waitcnt lgkmcnt(6)
	v_add_f32_e32 v203, v212, v203
	s_waitcnt lgkmcnt(5)
	v_add_f32_e32 v204, v71, v204
	s_waitcnt lgkmcnt(4)
	v_add_f32_e32 v205, v213, v205
	s_waitcnt lgkmcnt(3)
	v_add_f32_e32 v206, v214, v218
	s_waitcnt lgkmcnt(2)
	v_add_f32_e32 v207, v215, v219
	s_waitcnt lgkmcnt(1)
	v_add_f32_e32 v208, v216, v220
	s_waitcnt lgkmcnt(0)
	v_add_f32_e32 v209, v217, v221
	ds_bpermute_b32 v210, v185, v149
	ds_bpermute_b32 v211, v185, v176
	ds_bpermute_b32 v212, v185, v177
	ds_bpermute_b32 v213, v185, v178
	ds_bpermute_b32 v214, v185, v179
	ds_bpermute_b32 v215, v185, v180
	ds_bpermute_b32 v216, v185, v181
	ds_bpermute_b32 v217, v185, v201
	ds_bpermute_b32 v218, v185, v202
	ds_bpermute_b32 v219, v185, v203
	ds_bpermute_b32 v220, v185, v204
	ds_bpermute_b32 v221, v185, v205
	ds_bpermute_b32 v222, v185, v206
	ds_bpermute_b32 v223, v185, v207
	ds_bpermute_b32 v224, v185, v208
	ds_bpermute_b32 v225, v185, v209
	s_cbranch_vccnz .LBB0_483
	s_movk_i32 s0, 0x100
	s_waitcnt vmcnt(0)
	v_cmp_gt_u32_e64 s[28:29], s0, v244
